# sel: top-256 radix descent rewritten branch-free per bit (SGPR-mask v_bitop3 updates, same algorithm and register interface), on top of att K-offset reuse for V loads
# speedup vs baseline: 1.0064x; 1.0043x over previous
.LBB0_843:
	s_lshl_b32 s6, s12, 10
	s_add_i32 s40, s6, 0
	s_add_i32 s40, s40, 0x20000
	s_add_i32 s41, s41, s12
	s_cmpk_gt_i32 s19, 0x100
	s_mov_b64 s[6:7], -1
	s_cbranch_scc0 .LBB0_1135
	v_xad_u32 v0, v99, 63, s19
	v_lshrrev_b32_e32 v1, 6, v0
	v_lshlrev_b32_e64 v2, v1, -1
	v_not_b32_e32 v2, v2
	v_cmp_gt_u32_e32 vcc, s49, v0
	v_subrev_u32_e32 v8, 32, v1
	v_lshlrev_b32_e64 v8, v8, -1
	v_cndmask_b32_e32 v7, -1, v2, vcc
	v_not_b32_e32 v8, v8
	v_cmp_lt_u32_e32 vcc, s50, v0
	v_subrev_u32_e32 v9, 64, v1
	v_lshlrev_b32_e64 v9, v9, -1
	v_cndmask_b32_e32 v8, 0, v8, vcc
	v_cmp_gt_u32_e32 vcc, s27, v0
	v_not_b32_e32 v9, v9
	v_add_u32_e32 v1, 0xffffffa0, v1
	v_cndmask_b32_e32 v6, -1, v8, vcc
	v_cmp_lt_u32_e32 vcc, s51, v0
	v_lshlrev_b32_e64 v1, v1, -1
	v_not_b32_e32 v1, v1
	v_cndmask_b32_e32 v9, 0, v9, vcc
	v_cmp_gt_u32_e32 vcc, s52, v0
	s_mov_b32 s57, 0
	v_mov_b32_e32 v3, 0
	v_cndmask_b32_e32 v5, -1, v9, vcc
	v_cmp_lt_u32_e32 vcc, s53, v0
	v_mov_b32_e32 v2, 0
	s_nop 0
	v_cndmask_b32_e32 v1, 0, v1, vcc
	v_cmp_gt_u32_e32 vcc, s48, v0
	v_mov_b32_e32 v0, 0
	s_nop 0
	v_cndmask_b32_e32 v4, -1, v1, vcc
	v_mov_b32_e32 v1, 0
	v_and_b32_e32 v8, v7, v189
	v_and_b32_e32 v9, v6, v186
	v_bcnt_u32_b32 v12, v8, 0
	v_and_b32_e32 v10, v5, v95
	v_bcnt_u32_b32 v12, v9, v12
	v_and_b32_e32 v11, v4, v92
	v_bcnt_u32_b32 v12, v10, v12
	v_bcnt_u32_b32 v12, v11, v12
	s_nop 1
	v_add_u32_dpp v12, v12, v12 row_ror:8 row_mask:0xf bank_mask:0xf bound_ctrl:1
	s_nop 1
	v_add_u32_dpp v12, v12, v12 row_ror:4 row_mask:0xf bank_mask:0xf bound_ctrl:1
	s_nop 1
	v_add_u32_dpp v12, v12, v12 row_ror:2 row_mask:0xf bank_mask:0xf bound_ctrl:1
	s_nop 1
	v_add_u32_dpp v12, v12, v12 row_ror:1 row_mask:0xf bank_mask:0xf bound_ctrl:1
	s_nop 0
	v_readlane_b32 s6, v12, 0
	v_readlane_b32 s7, v12, 16
	v_readlane_b32 s8, v12, 32
	v_readlane_b32 s9, v12, 48
	s_add_i32 s6, s6, s7
	s_add_i32 s8, s8, s9
	s_add_i32 s6, s6, s57
	s_add_i32 s8, s6, s8
	s_cmpk_eq_i32 s8, 0x100
	s_cbranch_scc1 .Lrdx_eq
	s_cmpk_lt_i32 s8, 0x100
	s_cselect_b32 s6, -1, 0
	s_cselect_b32 s57, s8, s57
	v_bitop3_b32 v7, v7, v189, s6 bitop3:0x60
	v_bitop3_b32 v6, v6, v186, s6 bitop3:0x60
	v_bitop3_b32 v5, v5, v95, s6 bitop3:0x60
	v_bitop3_b32 v4, v4, v92, s6 bitop3:0x60
	v_bitop3_b32 v3, v3, v8, s6 bitop3:0xf8
	v_bitop3_b32 v2, v2, v9, s6 bitop3:0xf8
	v_bitop3_b32 v1, v1, v10, s6 bitop3:0xf8
	v_bitop3_b32 v0, v0, v11, s6 bitop3:0xf8
	v_and_b32_e32 v8, v7, v188
	v_and_b32_e32 v9, v6, v185
	v_bcnt_u32_b32 v12, v8, 0
	v_and_b32_e32 v10, v5, v94
	v_bcnt_u32_b32 v12, v9, v12
	v_and_b32_e32 v11, v4, v90
	v_bcnt_u32_b32 v12, v10, v12
	v_bcnt_u32_b32 v12, v11, v12
	s_nop 1
	v_add_u32_dpp v12, v12, v12 row_ror:8 row_mask:0xf bank_mask:0xf bound_ctrl:1
	s_nop 1
	v_add_u32_dpp v12, v12, v12 row_ror:4 row_mask:0xf bank_mask:0xf bound_ctrl:1
	s_nop 1
	v_add_u32_dpp v12, v12, v12 row_ror:2 row_mask:0xf bank_mask:0xf bound_ctrl:1
	s_nop 1
	v_add_u32_dpp v12, v12, v12 row_ror:1 row_mask:0xf bank_mask:0xf bound_ctrl:1
	s_nop 0
	v_readlane_b32 s6, v12, 0
	v_readlane_b32 s7, v12, 16
	v_readlane_b32 s8, v12, 32
	v_readlane_b32 s9, v12, 48
	s_add_i32 s6, s6, s7
	s_add_i32 s8, s8, s9
	s_add_i32 s6, s6, s57
	s_add_i32 s8, s6, s8
	s_cmpk_eq_i32 s8, 0x100
	s_cbranch_scc1 .Lrdx_eq
	s_cmpk_lt_i32 s8, 0x100
	s_cselect_b32 s6, -1, 0
	s_cselect_b32 s57, s8, s57
	v_bitop3_b32 v7, v7, v188, s6 bitop3:0x60
	v_bitop3_b32 v6, v6, v185, s6 bitop3:0x60
	v_bitop3_b32 v5, v5, v94, s6 bitop3:0x60
	v_bitop3_b32 v4, v4, v90, s6 bitop3:0x60
	v_bitop3_b32 v3, v3, v8, s6 bitop3:0xf8
	v_bitop3_b32 v2, v2, v9, s6 bitop3:0xf8
	v_bitop3_b32 v1, v1, v10, s6 bitop3:0xf8
	v_bitop3_b32 v0, v0, v11, s6 bitop3:0xf8
	v_and_b32_e32 v8, v7, v187
	v_and_b32_e32 v9, v6, v183
	v_bcnt_u32_b32 v12, v8, 0
	v_and_b32_e32 v10, v5, v93
	v_bcnt_u32_b32 v12, v9, v12
	v_and_b32_e32 v11, v4, v88
	v_bcnt_u32_b32 v12, v10, v12
	v_bcnt_u32_b32 v12, v11, v12
	s_nop 1
	v_add_u32_dpp v12, v12, v12 row_ror:8 row_mask:0xf bank_mask:0xf bound_ctrl:1
	s_nop 1
	v_add_u32_dpp v12, v12, v12 row_ror:4 row_mask:0xf bank_mask:0xf bound_ctrl:1
	s_nop 1
	v_add_u32_dpp v12, v12, v12 row_ror:2 row_mask:0xf bank_mask:0xf bound_ctrl:1
	s_nop 1
	v_add_u32_dpp v12, v12, v12 row_ror:1 row_mask:0xf bank_mask:0xf bound_ctrl:1
	s_nop 0
	v_readlane_b32 s6, v12, 0
	v_readlane_b32 s7, v12, 16
	v_readlane_b32 s8, v12, 32
	v_readlane_b32 s9, v12, 48
	s_add_i32 s6, s6, s7
	s_add_i32 s8, s8, s9
	s_add_i32 s6, s6, s57
	s_add_i32 s8, s6, s8
	s_cmpk_eq_i32 s8, 0x100
	s_cbranch_scc1 .Lrdx_eq
	s_cmpk_lt_i32 s8, 0x100
	s_cselect_b32 s6, -1, 0
	s_cselect_b32 s57, s8, s57
	v_bitop3_b32 v7, v7, v187, s6 bitop3:0x60
	v_bitop3_b32 v6, v6, v183, s6 bitop3:0x60
	v_bitop3_b32 v5, v5, v93, s6 bitop3:0x60
	v_bitop3_b32 v4, v4, v88, s6 bitop3:0x60
	v_bitop3_b32 v3, v3, v8, s6 bitop3:0xf8
	v_bitop3_b32 v2, v2, v9, s6 bitop3:0xf8
	v_bitop3_b32 v1, v1, v10, s6 bitop3:0xf8
	v_bitop3_b32 v0, v0, v11, s6 bitop3:0xf8
	v_and_b32_e32 v8, v7, v184
	v_and_b32_e32 v9, v6, v161
	v_bcnt_u32_b32 v12, v8, 0
	v_and_b32_e32 v10, v5, v91
	v_bcnt_u32_b32 v12, v9, v12
	v_and_b32_e32 v11, v4, v86
	v_bcnt_u32_b32 v12, v10, v12
	v_bcnt_u32_b32 v12, v11, v12
	s_nop 1
	v_add_u32_dpp v12, v12, v12 row_ror:8 row_mask:0xf bank_mask:0xf bound_ctrl:1
	s_nop 1
	v_add_u32_dpp v12, v12, v12 row_ror:4 row_mask:0xf bank_mask:0xf bound_ctrl:1
	s_nop 1
	v_add_u32_dpp v12, v12, v12 row_ror:2 row_mask:0xf bank_mask:0xf bound_ctrl:1
	s_nop 1
	v_add_u32_dpp v12, v12, v12 row_ror:1 row_mask:0xf bank_mask:0xf bound_ctrl:1
	s_nop 0
	v_readlane_b32 s6, v12, 0
	v_readlane_b32 s7, v12, 16
	v_readlane_b32 s8, v12, 32
	v_readlane_b32 s9, v12, 48
	s_add_i32 s6, s6, s7
	s_add_i32 s8, s8, s9
	s_add_i32 s6, s6, s57
	s_add_i32 s8, s6, s8
	s_cmpk_eq_i32 s8, 0x100
	s_cbranch_scc1 .Lrdx_eq
	s_cmpk_lt_i32 s8, 0x100
	s_cselect_b32 s6, -1, 0
	s_cselect_b32 s57, s8, s57
	v_bitop3_b32 v7, v7, v184, s6 bitop3:0x60
	v_bitop3_b32 v6, v6, v161, s6 bitop3:0x60
	v_bitop3_b32 v5, v5, v91, s6 bitop3:0x60
	v_bitop3_b32 v4, v4, v86, s6 bitop3:0x60
	v_bitop3_b32 v3, v3, v8, s6 bitop3:0xf8
	v_bitop3_b32 v2, v2, v9, s6 bitop3:0xf8
	v_bitop3_b32 v1, v1, v10, s6 bitop3:0xf8
	v_bitop3_b32 v0, v0, v11, s6 bitop3:0xf8
	v_and_b32_e32 v8, v7, v181
	v_and_b32_e32 v9, v6, v159
	v_bcnt_u32_b32 v12, v8, 0
	v_and_b32_e32 v10, v5, v89
	v_bcnt_u32_b32 v12, v9, v12
	v_and_b32_e32 v11, v4, v84
	v_bcnt_u32_b32 v12, v10, v12
	v_bcnt_u32_b32 v12, v11, v12
	s_nop 1
	v_add_u32_dpp v12, v12, v12 row_ror:8 row_mask:0xf bank_mask:0xf bound_ctrl:1
	s_nop 1
	v_add_u32_dpp v12, v12, v12 row_ror:4 row_mask:0xf bank_mask:0xf bound_ctrl:1
	s_nop 1
	v_add_u32_dpp v12, v12, v12 row_ror:2 row_mask:0xf bank_mask:0xf bound_ctrl:1
	s_nop 1
	v_add_u32_dpp v12, v12, v12 row_ror:1 row_mask:0xf bank_mask:0xf bound_ctrl:1
	s_nop 0
	v_readlane_b32 s6, v12, 0
	v_readlane_b32 s7, v12, 16
	v_readlane_b32 s8, v12, 32
	v_readlane_b32 s9, v12, 48
	s_add_i32 s6, s6, s7
	s_add_i32 s8, s8, s9
	s_add_i32 s6, s6, s57
	s_add_i32 s8, s6, s8
	s_cmpk_eq_i32 s8, 0x100
	s_cbranch_scc1 .Lrdx_eq
	s_cmpk_lt_i32 s8, 0x100
	s_cselect_b32 s6, -1, 0
	s_cselect_b32 s57, s8, s57
	v_bitop3_b32 v7, v7, v181, s6 bitop3:0x60
	v_bitop3_b32 v6, v6, v159, s6 bitop3:0x60
	v_bitop3_b32 v5, v5, v89, s6 bitop3:0x60
	v_bitop3_b32 v4, v4, v84, s6 bitop3:0x60
	v_bitop3_b32 v3, v3, v8, s6 bitop3:0xf8
	v_bitop3_b32 v2, v2, v9, s6 bitop3:0xf8
	v_bitop3_b32 v1, v1, v10, s6 bitop3:0xf8
	v_bitop3_b32 v0, v0, v11, s6 bitop3:0xf8
	v_and_b32_e32 v8, v7, v160
	v_and_b32_e32 v9, v6, v157
	v_bcnt_u32_b32 v12, v8, 0
	v_and_b32_e32 v10, v5, v87
	v_bcnt_u32_b32 v12, v9, v12
	v_and_b32_e32 v11, v4, v82
	v_bcnt_u32_b32 v12, v10, v12
	v_bcnt_u32_b32 v12, v11, v12
	s_nop 1
	v_add_u32_dpp v12, v12, v12 row_ror:8 row_mask:0xf bank_mask:0xf bound_ctrl:1
	s_nop 1
	v_add_u32_dpp v12, v12, v12 row_ror:4 row_mask:0xf bank_mask:0xf bound_ctrl:1
	s_nop 1
	v_add_u32_dpp v12, v12, v12 row_ror:2 row_mask:0xf bank_mask:0xf bound_ctrl:1
	s_nop 1
	v_add_u32_dpp v12, v12, v12 row_ror:1 row_mask:0xf bank_mask:0xf bound_ctrl:1
	s_nop 0
	v_readlane_b32 s6, v12, 0
	v_readlane_b32 s7, v12, 16
	v_readlane_b32 s8, v12, 32
	v_readlane_b32 s9, v12, 48
	s_add_i32 s6, s6, s7
	s_add_i32 s8, s8, s9
	s_add_i32 s6, s6, s57
	s_add_i32 s8, s6, s8
	s_cmpk_eq_i32 s8, 0x100
	s_cbranch_scc1 .Lrdx_eq
	s_cmpk_lt_i32 s8, 0x100
	s_cselect_b32 s6, -1, 0
	s_cselect_b32 s57, s8, s57
	v_bitop3_b32 v7, v7, v160, s6 bitop3:0x60
	v_bitop3_b32 v6, v6, v157, s6 bitop3:0x60
	v_bitop3_b32 v5, v5, v87, s6 bitop3:0x60
	v_bitop3_b32 v4, v4, v82, s6 bitop3:0x60
	v_bitop3_b32 v3, v3, v8, s6 bitop3:0xf8
	v_bitop3_b32 v2, v2, v9, s6 bitop3:0xf8
	v_bitop3_b32 v1, v1, v10, s6 bitop3:0xf8
	v_bitop3_b32 v0, v0, v11, s6 bitop3:0xf8
	v_and_b32_e32 v8, v7, v158
	v_and_b32_e32 v9, v6, v155
	v_bcnt_u32_b32 v12, v8, 0
	v_and_b32_e32 v10, v5, v85
	v_bcnt_u32_b32 v12, v9, v12
	v_and_b32_e32 v11, v4, v80
	v_bcnt_u32_b32 v12, v10, v12
	v_bcnt_u32_b32 v12, v11, v12
	s_nop 1
	v_add_u32_dpp v12, v12, v12 row_ror:8 row_mask:0xf bank_mask:0xf bound_ctrl:1
	s_nop 1
	v_add_u32_dpp v12, v12, v12 row_ror:4 row_mask:0xf bank_mask:0xf bound_ctrl:1
	s_nop 1
	v_add_u32_dpp v12, v12, v12 row_ror:2 row_mask:0xf bank_mask:0xf bound_ctrl:1
	s_nop 1
	v_add_u32_dpp v12, v12, v12 row_ror:1 row_mask:0xf bank_mask:0xf bound_ctrl:1
	s_nop 0
	v_readlane_b32 s6, v12, 0
	v_readlane_b32 s7, v12, 16
	v_readlane_b32 s8, v12, 32
	v_readlane_b32 s9, v12, 48
	s_add_i32 s6, s6, s7
	s_add_i32 s8, s8, s9
	s_add_i32 s6, s6, s57
	s_add_i32 s8, s6, s8
	s_cmpk_eq_i32 s8, 0x100
	s_cbranch_scc1 .Lrdx_eq
	s_cmpk_lt_i32 s8, 0x100
	s_cselect_b32 s6, -1, 0
	s_cselect_b32 s57, s8, s57
	v_bitop3_b32 v7, v7, v158, s6 bitop3:0x60
	v_bitop3_b32 v6, v6, v155, s6 bitop3:0x60
	v_bitop3_b32 v5, v5, v85, s6 bitop3:0x60
	v_bitop3_b32 v4, v4, v80, s6 bitop3:0x60
	v_bitop3_b32 v3, v3, v8, s6 bitop3:0xf8
	v_bitop3_b32 v2, v2, v9, s6 bitop3:0xf8
	v_bitop3_b32 v1, v1, v10, s6 bitop3:0xf8
	v_bitop3_b32 v0, v0, v11, s6 bitop3:0xf8
	v_and_b32_e32 v8, v7, v156
	v_and_b32_e32 v9, v6, v153
	v_bcnt_u32_b32 v12, v8, 0
	v_and_b32_e32 v10, v5, v83
	v_bcnt_u32_b32 v12, v9, v12
	v_and_b32_e32 v11, v4, v78
	v_bcnt_u32_b32 v12, v10, v12
	v_bcnt_u32_b32 v12, v11, v12
	s_nop 1
	v_add_u32_dpp v12, v12, v12 row_ror:8 row_mask:0xf bank_mask:0xf bound_ctrl:1
	s_nop 1
	v_add_u32_dpp v12, v12, v12 row_ror:4 row_mask:0xf bank_mask:0xf bound_ctrl:1
	s_nop 1
	v_add_u32_dpp v12, v12, v12 row_ror:2 row_mask:0xf bank_mask:0xf bound_ctrl:1
	s_nop 1
	v_add_u32_dpp v12, v12, v12 row_ror:1 row_mask:0xf bank_mask:0xf bound_ctrl:1
	s_nop 0
	v_readlane_b32 s6, v12, 0
	v_readlane_b32 s7, v12, 16
	v_readlane_b32 s8, v12, 32
	v_readlane_b32 s9, v12, 48
	s_add_i32 s6, s6, s7
	s_add_i32 s8, s8, s9
	s_add_i32 s6, s6, s57
	s_add_i32 s8, s6, s8
	s_cmpk_eq_i32 s8, 0x100
	s_cbranch_scc1 .Lrdx_eq
	s_cmpk_lt_i32 s8, 0x100
	s_cselect_b32 s6, -1, 0
	s_cselect_b32 s57, s8, s57
	v_bitop3_b32 v7, v7, v156, s6 bitop3:0x60
	v_bitop3_b32 v6, v6, v153, s6 bitop3:0x60
	v_bitop3_b32 v5, v5, v83, s6 bitop3:0x60
	v_bitop3_b32 v4, v4, v78, s6 bitop3:0x60
	v_bitop3_b32 v3, v3, v8, s6 bitop3:0xf8
	v_bitop3_b32 v2, v2, v9, s6 bitop3:0xf8
	v_bitop3_b32 v1, v1, v10, s6 bitop3:0xf8
	v_bitop3_b32 v0, v0, v11, s6 bitop3:0xf8
	v_and_b32_e32 v8, v7, v154
	v_and_b32_e32 v9, v6, v151
	v_bcnt_u32_b32 v12, v8, 0
	v_and_b32_e32 v10, v5, v81
	v_bcnt_u32_b32 v12, v9, v12
	v_and_b32_e32 v11, v4, v76
	v_bcnt_u32_b32 v12, v10, v12
	v_bcnt_u32_b32 v12, v11, v12
	s_nop 1
	v_add_u32_dpp v12, v12, v12 row_ror:8 row_mask:0xf bank_mask:0xf bound_ctrl:1
	s_nop 1
	v_add_u32_dpp v12, v12, v12 row_ror:4 row_mask:0xf bank_mask:0xf bound_ctrl:1
	s_nop 1
	v_add_u32_dpp v12, v12, v12 row_ror:2 row_mask:0xf bank_mask:0xf bound_ctrl:1
	s_nop 1
	v_add_u32_dpp v12, v12, v12 row_ror:1 row_mask:0xf bank_mask:0xf bound_ctrl:1
	s_nop 0
	v_readlane_b32 s6, v12, 0
	v_readlane_b32 s7, v12, 16
	v_readlane_b32 s8, v12, 32
	v_readlane_b32 s9, v12, 48
	s_add_i32 s6, s6, s7
	s_add_i32 s8, s8, s9
	s_add_i32 s6, s6, s57
	s_add_i32 s8, s6, s8
	s_cmpk_eq_i32 s8, 0x100
	s_cbranch_scc1 .Lrdx_eq
	s_cmpk_lt_i32 s8, 0x100
	s_cselect_b32 s6, -1, 0
	s_cselect_b32 s57, s8, s57
	v_bitop3_b32 v7, v7, v154, s6 bitop3:0x60
	v_bitop3_b32 v6, v6, v151, s6 bitop3:0x60
	v_bitop3_b32 v5, v5, v81, s6 bitop3:0x60
	v_bitop3_b32 v4, v4, v76, s6 bitop3:0x60
	v_bitop3_b32 v3, v3, v8, s6 bitop3:0xf8
	v_bitop3_b32 v2, v2, v9, s6 bitop3:0xf8
	v_bitop3_b32 v1, v1, v10, s6 bitop3:0xf8
	v_bitop3_b32 v0, v0, v11, s6 bitop3:0xf8
	v_and_b32_e32 v8, v7, v152
	v_and_b32_e32 v9, v6, v149
	v_bcnt_u32_b32 v12, v8, 0
	v_and_b32_e32 v10, v5, v79
	v_bcnt_u32_b32 v12, v9, v12
	v_and_b32_e32 v11, v4, v74
	v_bcnt_u32_b32 v12, v10, v12
	v_bcnt_u32_b32 v12, v11, v12
	s_nop 1
	v_add_u32_dpp v12, v12, v12 row_ror:8 row_mask:0xf bank_mask:0xf bound_ctrl:1
	s_nop 1
	v_add_u32_dpp v12, v12, v12 row_ror:4 row_mask:0xf bank_mask:0xf bound_ctrl:1
	s_nop 1
	v_add_u32_dpp v12, v12, v12 row_ror:2 row_mask:0xf bank_mask:0xf bound_ctrl:1
	s_nop 1
	v_add_u32_dpp v12, v12, v12 row_ror:1 row_mask:0xf bank_mask:0xf bound_ctrl:1
	s_nop 0
	v_readlane_b32 s6, v12, 0
	v_readlane_b32 s7, v12, 16
	v_readlane_b32 s8, v12, 32
	v_readlane_b32 s9, v12, 48
	s_add_i32 s6, s6, s7
	s_add_i32 s8, s8, s9
	s_add_i32 s6, s6, s57
	s_add_i32 s8, s6, s8
	s_cmpk_eq_i32 s8, 0x100
	s_cbranch_scc1 .Lrdx_eq
	s_cmpk_lt_i32 s8, 0x100
	s_cselect_b32 s6, -1, 0
	s_cselect_b32 s57, s8, s57
	v_bitop3_b32 v7, v7, v152, s6 bitop3:0x60
	v_bitop3_b32 v6, v6, v149, s6 bitop3:0x60
	v_bitop3_b32 v5, v5, v79, s6 bitop3:0x60
	v_bitop3_b32 v4, v4, v74, s6 bitop3:0x60
	v_bitop3_b32 v3, v3, v8, s6 bitop3:0xf8
	v_bitop3_b32 v2, v2, v9, s6 bitop3:0xf8
	v_bitop3_b32 v1, v1, v10, s6 bitop3:0xf8
	v_bitop3_b32 v0, v0, v11, s6 bitop3:0xf8
	v_and_b32_e32 v8, v7, v150
	v_and_b32_e32 v9, v6, v147
	v_bcnt_u32_b32 v12, v8, 0
	v_and_b32_e32 v10, v5, v77
	v_bcnt_u32_b32 v12, v9, v12
	v_and_b32_e32 v11, v4, v72
	v_bcnt_u32_b32 v12, v10, v12
	v_bcnt_u32_b32 v12, v11, v12
	s_nop 1
	v_add_u32_dpp v12, v12, v12 row_ror:8 row_mask:0xf bank_mask:0xf bound_ctrl:1
	s_nop 1
	v_add_u32_dpp v12, v12, v12 row_ror:4 row_mask:0xf bank_mask:0xf bound_ctrl:1
	s_nop 1
	v_add_u32_dpp v12, v12, v12 row_ror:2 row_mask:0xf bank_mask:0xf bound_ctrl:1
	s_nop 1
	v_add_u32_dpp v12, v12, v12 row_ror:1 row_mask:0xf bank_mask:0xf bound_ctrl:1
	s_nop 0
	v_readlane_b32 s6, v12, 0
	v_readlane_b32 s7, v12, 16
	v_readlane_b32 s8, v12, 32
	v_readlane_b32 s9, v12, 48
	s_add_i32 s6, s6, s7
	s_add_i32 s8, s8, s9
	s_add_i32 s6, s6, s57
	s_add_i32 s8, s6, s8
	s_cmpk_eq_i32 s8, 0x100
	s_cbranch_scc1 .Lrdx_eq
	s_cmpk_lt_i32 s8, 0x100
	s_cselect_b32 s6, -1, 0
	s_cselect_b32 s57, s8, s57
	v_bitop3_b32 v7, v7, v150, s6 bitop3:0x60
	v_bitop3_b32 v6, v6, v147, s6 bitop3:0x60
	v_bitop3_b32 v5, v5, v77, s6 bitop3:0x60
	v_bitop3_b32 v4, v4, v72, s6 bitop3:0x60
	v_bitop3_b32 v3, v3, v8, s6 bitop3:0xf8
	v_bitop3_b32 v2, v2, v9, s6 bitop3:0xf8
	v_bitop3_b32 v1, v1, v10, s6 bitop3:0xf8
	v_bitop3_b32 v0, v0, v11, s6 bitop3:0xf8
	v_and_b32_e32 v8, v7, v148
	v_and_b32_e32 v9, v6, v145
	v_bcnt_u32_b32 v12, v8, 0
	v_and_b32_e32 v10, v5, v75
	v_bcnt_u32_b32 v12, v9, v12
	v_and_b32_e32 v11, v4, v70
	v_bcnt_u32_b32 v12, v10, v12
	v_bcnt_u32_b32 v12, v11, v12
	s_nop 1
	v_add_u32_dpp v12, v12, v12 row_ror:8 row_mask:0xf bank_mask:0xf bound_ctrl:1
	s_nop 1
	v_add_u32_dpp v12, v12, v12 row_ror:4 row_mask:0xf bank_mask:0xf bound_ctrl:1
	s_nop 1
	v_add_u32_dpp v12, v12, v12 row_ror:2 row_mask:0xf bank_mask:0xf bound_ctrl:1
	s_nop 1
	v_add_u32_dpp v12, v12, v12 row_ror:1 row_mask:0xf bank_mask:0xf bound_ctrl:1
	s_nop 0
	v_readlane_b32 s6, v12, 0
	v_readlane_b32 s7, v12, 16
	v_readlane_b32 s8, v12, 32
	v_readlane_b32 s9, v12, 48
	s_add_i32 s6, s6, s7
	s_add_i32 s8, s8, s9
	s_add_i32 s6, s6, s57
	s_add_i32 s8, s6, s8
	s_cmpk_eq_i32 s8, 0x100
	s_cbranch_scc1 .Lrdx_eq
	s_cmpk_lt_i32 s8, 0x100
	s_cselect_b32 s6, -1, 0
	s_cselect_b32 s57, s8, s57
	v_bitop3_b32 v7, v7, v148, s6 bitop3:0x60
	v_bitop3_b32 v6, v6, v145, s6 bitop3:0x60
	v_bitop3_b32 v5, v5, v75, s6 bitop3:0x60
	v_bitop3_b32 v4, v4, v70, s6 bitop3:0x60
	v_bitop3_b32 v3, v3, v8, s6 bitop3:0xf8
	v_bitop3_b32 v2, v2, v9, s6 bitop3:0xf8
	v_bitop3_b32 v1, v1, v10, s6 bitop3:0xf8
	v_bitop3_b32 v0, v0, v11, s6 bitop3:0xf8
	v_and_b32_e32 v8, v7, v146
	v_and_b32_e32 v9, v6, v143
	v_bcnt_u32_b32 v12, v8, 0
	v_and_b32_e32 v10, v5, v73
	v_bcnt_u32_b32 v12, v9, v12
	v_and_b32_e32 v11, v4, v68
	v_bcnt_u32_b32 v12, v10, v12
	v_bcnt_u32_b32 v12, v11, v12
	s_nop 1
	v_add_u32_dpp v12, v12, v12 row_ror:8 row_mask:0xf bank_mask:0xf bound_ctrl:1
	s_nop 1
	v_add_u32_dpp v12, v12, v12 row_ror:4 row_mask:0xf bank_mask:0xf bound_ctrl:1
	s_nop 1
	v_add_u32_dpp v12, v12, v12 row_ror:2 row_mask:0xf bank_mask:0xf bound_ctrl:1
	s_nop 1
	v_add_u32_dpp v12, v12, v12 row_ror:1 row_mask:0xf bank_mask:0xf bound_ctrl:1
	s_nop 0
	v_readlane_b32 s6, v12, 0
	v_readlane_b32 s7, v12, 16
	v_readlane_b32 s8, v12, 32
	v_readlane_b32 s9, v12, 48
	s_add_i32 s6, s6, s7
	s_add_i32 s8, s8, s9
	s_add_i32 s6, s6, s57
	s_add_i32 s8, s6, s8
	s_cmpk_eq_i32 s8, 0x100
	s_cbranch_scc1 .Lrdx_eq
	s_cmpk_lt_i32 s8, 0x100
	s_cselect_b32 s6, -1, 0
	s_cselect_b32 s57, s8, s57
	v_bitop3_b32 v7, v7, v146, s6 bitop3:0x60
	v_bitop3_b32 v6, v6, v143, s6 bitop3:0x60
	v_bitop3_b32 v5, v5, v73, s6 bitop3:0x60
	v_bitop3_b32 v4, v4, v68, s6 bitop3:0x60
	v_bitop3_b32 v3, v3, v8, s6 bitop3:0xf8
	v_bitop3_b32 v2, v2, v9, s6 bitop3:0xf8
	v_bitop3_b32 v1, v1, v10, s6 bitop3:0xf8
	v_bitop3_b32 v0, v0, v11, s6 bitop3:0xf8
	v_and_b32_e32 v8, v7, v144
	v_and_b32_e32 v9, v6, v141
	v_bcnt_u32_b32 v12, v8, 0
	v_and_b32_e32 v10, v5, v71
	v_bcnt_u32_b32 v12, v9, v12
	v_and_b32_e32 v11, v4, v66
	v_bcnt_u32_b32 v12, v10, v12
	v_bcnt_u32_b32 v12, v11, v12
	s_nop 1
	v_add_u32_dpp v12, v12, v12 row_ror:8 row_mask:0xf bank_mask:0xf bound_ctrl:1
	s_nop 1
	v_add_u32_dpp v12, v12, v12 row_ror:4 row_mask:0xf bank_mask:0xf bound_ctrl:1
	s_nop 1
	v_add_u32_dpp v12, v12, v12 row_ror:2 row_mask:0xf bank_mask:0xf bound_ctrl:1
	s_nop 1
	v_add_u32_dpp v12, v12, v12 row_ror:1 row_mask:0xf bank_mask:0xf bound_ctrl:1
	s_nop 0
	v_readlane_b32 s6, v12, 0
	v_readlane_b32 s7, v12, 16
	v_readlane_b32 s8, v12, 32
	v_readlane_b32 s9, v12, 48
	s_add_i32 s6, s6, s7
	s_add_i32 s8, s8, s9
	s_add_i32 s6, s6, s57
	s_add_i32 s8, s6, s8
	s_cmpk_eq_i32 s8, 0x100
	s_cbranch_scc1 .Lrdx_eq
	s_cmpk_lt_i32 s8, 0x100
	s_cselect_b32 s6, -1, 0
	s_cselect_b32 s57, s8, s57
	v_bitop3_b32 v7, v7, v144, s6 bitop3:0x60
	v_bitop3_b32 v6, v6, v141, s6 bitop3:0x60
	v_bitop3_b32 v5, v5, v71, s6 bitop3:0x60
	v_bitop3_b32 v4, v4, v66, s6 bitop3:0x60
	v_bitop3_b32 v3, v3, v8, s6 bitop3:0xf8
	v_bitop3_b32 v2, v2, v9, s6 bitop3:0xf8
	v_bitop3_b32 v1, v1, v10, s6 bitop3:0xf8
	v_bitop3_b32 v0, v0, v11, s6 bitop3:0xf8
	v_and_b32_e32 v8, v7, v142
	v_and_b32_e32 v9, v6, v139
	v_bcnt_u32_b32 v12, v8, 0
	v_and_b32_e32 v10, v5, v69
	v_bcnt_u32_b32 v12, v9, v12
	v_and_b32_e32 v11, v4, v64
	v_bcnt_u32_b32 v12, v10, v12
	v_bcnt_u32_b32 v12, v11, v12
	s_nop 1
	v_add_u32_dpp v12, v12, v12 row_ror:8 row_mask:0xf bank_mask:0xf bound_ctrl:1
	s_nop 1
	v_add_u32_dpp v12, v12, v12 row_ror:4 row_mask:0xf bank_mask:0xf bound_ctrl:1
	s_nop 1
	v_add_u32_dpp v12, v12, v12 row_ror:2 row_mask:0xf bank_mask:0xf bound_ctrl:1
	s_nop 1
	v_add_u32_dpp v12, v12, v12 row_ror:1 row_mask:0xf bank_mask:0xf bound_ctrl:1
	s_nop 0
	v_readlane_b32 s6, v12, 0
	v_readlane_b32 s7, v12, 16
	v_readlane_b32 s8, v12, 32
	v_readlane_b32 s9, v12, 48
	s_add_i32 s6, s6, s7
	s_add_i32 s8, s8, s9
	s_add_i32 s6, s6, s57
	s_add_i32 s8, s6, s8
	s_cmpk_eq_i32 s8, 0x100
	s_cbranch_scc1 .Lrdx_eq
	s_cmpk_lt_i32 s8, 0x100
	s_cselect_b32 s6, -1, 0
	s_cselect_b32 s57, s8, s57
	v_bitop3_b32 v7, v7, v142, s6 bitop3:0x60
	v_bitop3_b32 v6, v6, v139, s6 bitop3:0x60
	v_bitop3_b32 v5, v5, v69, s6 bitop3:0x60
	v_bitop3_b32 v4, v4, v64, s6 bitop3:0x60
	v_bitop3_b32 v3, v3, v8, s6 bitop3:0xf8
	v_bitop3_b32 v2, v2, v9, s6 bitop3:0xf8
	v_bitop3_b32 v1, v1, v10, s6 bitop3:0xf8
	v_bitop3_b32 v0, v0, v11, s6 bitop3:0xf8
	v_and_b32_e32 v8, v7, v140
	v_and_b32_e32 v9, v6, v137
	v_bcnt_u32_b32 v12, v8, 0
	v_and_b32_e32 v10, v5, v67
	v_bcnt_u32_b32 v12, v9, v12
	v_and_b32_e32 v11, v4, v62
	v_bcnt_u32_b32 v12, v10, v12
	v_bcnt_u32_b32 v12, v11, v12
	s_nop 1
	v_add_u32_dpp v12, v12, v12 row_ror:8 row_mask:0xf bank_mask:0xf bound_ctrl:1
	s_nop 1
	v_add_u32_dpp v12, v12, v12 row_ror:4 row_mask:0xf bank_mask:0xf bound_ctrl:1
	s_nop 1
	v_add_u32_dpp v12, v12, v12 row_ror:2 row_mask:0xf bank_mask:0xf bound_ctrl:1
	s_nop 1
	v_add_u32_dpp v12, v12, v12 row_ror:1 row_mask:0xf bank_mask:0xf bound_ctrl:1
	s_nop 0
	v_readlane_b32 s6, v12, 0
	v_readlane_b32 s7, v12, 16
	v_readlane_b32 s8, v12, 32
	v_readlane_b32 s9, v12, 48
	s_add_i32 s6, s6, s7
	s_add_i32 s8, s8, s9
	s_add_i32 s6, s6, s57
	s_add_i32 s8, s6, s8
	s_cmpk_eq_i32 s8, 0x100
	s_cbranch_scc1 .Lrdx_eq
	s_cmpk_lt_i32 s8, 0x100
	s_cselect_b32 s6, -1, 0
	s_cselect_b32 s57, s8, s57
	v_bitop3_b32 v7, v7, v140, s6 bitop3:0x60
	v_bitop3_b32 v6, v6, v137, s6 bitop3:0x60
	v_bitop3_b32 v5, v5, v67, s6 bitop3:0x60
	v_bitop3_b32 v4, v4, v62, s6 bitop3:0x60
	v_bitop3_b32 v3, v3, v8, s6 bitop3:0xf8
	v_bitop3_b32 v2, v2, v9, s6 bitop3:0xf8
	v_bitop3_b32 v1, v1, v10, s6 bitop3:0xf8
	v_bitop3_b32 v0, v0, v11, s6 bitop3:0xf8
	v_and_b32_e32 v8, v7, v138
	v_and_b32_e32 v9, v6, v135
	v_bcnt_u32_b32 v12, v8, 0
	v_and_b32_e32 v10, v5, v65
	v_bcnt_u32_b32 v12, v9, v12
	v_and_b32_e32 v11, v4, v60
	v_bcnt_u32_b32 v12, v10, v12
	v_bcnt_u32_b32 v12, v11, v12
	s_nop 1
	v_add_u32_dpp v12, v12, v12 row_ror:8 row_mask:0xf bank_mask:0xf bound_ctrl:1
	s_nop 1
	v_add_u32_dpp v12, v12, v12 row_ror:4 row_mask:0xf bank_mask:0xf bound_ctrl:1
	s_nop 1
	v_add_u32_dpp v12, v12, v12 row_ror:2 row_mask:0xf bank_mask:0xf bound_ctrl:1
	s_nop 1
	v_add_u32_dpp v12, v12, v12 row_ror:1 row_mask:0xf bank_mask:0xf bound_ctrl:1
	s_nop 0
	v_readlane_b32 s6, v12, 0
	v_readlane_b32 s7, v12, 16
	v_readlane_b32 s8, v12, 32
	v_readlane_b32 s9, v12, 48
	s_add_i32 s6, s6, s7
	s_add_i32 s8, s8, s9
	s_add_i32 s6, s6, s57
	s_add_i32 s8, s6, s8
	s_cmpk_eq_i32 s8, 0x100
	s_cbranch_scc1 .Lrdx_eq
	s_cmpk_lt_i32 s8, 0x100
	s_cselect_b32 s6, -1, 0
	s_cselect_b32 s57, s8, s57
	v_bitop3_b32 v7, v7, v138, s6 bitop3:0x60
	v_bitop3_b32 v6, v6, v135, s6 bitop3:0x60
	v_bitop3_b32 v5, v5, v65, s6 bitop3:0x60
	v_bitop3_b32 v4, v4, v60, s6 bitop3:0x60
	v_bitop3_b32 v3, v3, v8, s6 bitop3:0xf8
	v_bitop3_b32 v2, v2, v9, s6 bitop3:0xf8
	v_bitop3_b32 v1, v1, v10, s6 bitop3:0xf8
	v_bitop3_b32 v0, v0, v11, s6 bitop3:0xf8
	v_and_b32_e32 v8, v7, v136
	v_and_b32_e32 v9, v6, v133
	v_bcnt_u32_b32 v12, v8, 0
	v_and_b32_e32 v10, v5, v63
	v_bcnt_u32_b32 v12, v9, v12
	v_and_b32_e32 v11, v4, v58
	v_bcnt_u32_b32 v12, v10, v12
	v_bcnt_u32_b32 v12, v11, v12
	s_nop 1
	v_add_u32_dpp v12, v12, v12 row_ror:8 row_mask:0xf bank_mask:0xf bound_ctrl:1
	s_nop 1
	v_add_u32_dpp v12, v12, v12 row_ror:4 row_mask:0xf bank_mask:0xf bound_ctrl:1
	s_nop 1
	v_add_u32_dpp v12, v12, v12 row_ror:2 row_mask:0xf bank_mask:0xf bound_ctrl:1
	s_nop 1
	v_add_u32_dpp v12, v12, v12 row_ror:1 row_mask:0xf bank_mask:0xf bound_ctrl:1
	s_nop 0
	v_readlane_b32 s6, v12, 0
	v_readlane_b32 s7, v12, 16
	v_readlane_b32 s8, v12, 32
	v_readlane_b32 s9, v12, 48
	s_add_i32 s6, s6, s7
	s_add_i32 s8, s8, s9
	s_add_i32 s6, s6, s57
	s_add_i32 s8, s6, s8
	s_cmpk_eq_i32 s8, 0x100
	s_cbranch_scc1 .Lrdx_eq
	s_cmpk_lt_i32 s8, 0x100
	s_cselect_b32 s6, -1, 0
	s_cselect_b32 s57, s8, s57
	v_bitop3_b32 v7, v7, v136, s6 bitop3:0x60
	v_bitop3_b32 v6, v6, v133, s6 bitop3:0x60
	v_bitop3_b32 v5, v5, v63, s6 bitop3:0x60
	v_bitop3_b32 v4, v4, v58, s6 bitop3:0x60
	v_bitop3_b32 v3, v3, v8, s6 bitop3:0xf8
	v_bitop3_b32 v2, v2, v9, s6 bitop3:0xf8
	v_bitop3_b32 v1, v1, v10, s6 bitop3:0xf8
	v_bitop3_b32 v0, v0, v11, s6 bitop3:0xf8
	v_and_b32_e32 v8, v7, v134
	v_and_b32_e32 v9, v6, v131
	v_bcnt_u32_b32 v12, v8, 0
	v_and_b32_e32 v10, v5, v61
	v_bcnt_u32_b32 v12, v9, v12
	v_and_b32_e32 v11, v4, v56
	v_bcnt_u32_b32 v12, v10, v12
	v_bcnt_u32_b32 v12, v11, v12
	s_nop 1
	v_add_u32_dpp v12, v12, v12 row_ror:8 row_mask:0xf bank_mask:0xf bound_ctrl:1
	s_nop 1
	v_add_u32_dpp v12, v12, v12 row_ror:4 row_mask:0xf bank_mask:0xf bound_ctrl:1
	s_nop 1
	v_add_u32_dpp v12, v12, v12 row_ror:2 row_mask:0xf bank_mask:0xf bound_ctrl:1
	s_nop 1
	v_add_u32_dpp v12, v12, v12 row_ror:1 row_mask:0xf bank_mask:0xf bound_ctrl:1
	s_nop 0
	v_readlane_b32 s6, v12, 0
	v_readlane_b32 s7, v12, 16
	v_readlane_b32 s8, v12, 32
	v_readlane_b32 s9, v12, 48
	s_add_i32 s6, s6, s7
	s_add_i32 s8, s8, s9
	s_add_i32 s6, s6, s57
	s_add_i32 s8, s6, s8
	s_cmpk_eq_i32 s8, 0x100
	s_cbranch_scc1 .Lrdx_eq
	s_cmpk_lt_i32 s8, 0x100
	s_cselect_b32 s6, -1, 0
	s_cselect_b32 s57, s8, s57
	v_bitop3_b32 v7, v7, v134, s6 bitop3:0x60
	v_bitop3_b32 v6, v6, v131, s6 bitop3:0x60
	v_bitop3_b32 v5, v5, v61, s6 bitop3:0x60
	v_bitop3_b32 v4, v4, v56, s6 bitop3:0x60
	v_bitop3_b32 v3, v3, v8, s6 bitop3:0xf8
	v_bitop3_b32 v2, v2, v9, s6 bitop3:0xf8
	v_bitop3_b32 v1, v1, v10, s6 bitop3:0xf8
	v_bitop3_b32 v0, v0, v11, s6 bitop3:0xf8
	v_and_b32_e32 v8, v7, v132
	v_and_b32_e32 v9, v6, v129
	v_bcnt_u32_b32 v12, v8, 0
	v_and_b32_e32 v10, v5, v59
	v_bcnt_u32_b32 v12, v9, v12
	v_and_b32_e32 v11, v4, v54
	v_bcnt_u32_b32 v12, v10, v12
	v_bcnt_u32_b32 v12, v11, v12
	s_nop 1
	v_add_u32_dpp v12, v12, v12 row_ror:8 row_mask:0xf bank_mask:0xf bound_ctrl:1
	s_nop 1
	v_add_u32_dpp v12, v12, v12 row_ror:4 row_mask:0xf bank_mask:0xf bound_ctrl:1
	s_nop 1
	v_add_u32_dpp v12, v12, v12 row_ror:2 row_mask:0xf bank_mask:0xf bound_ctrl:1
	s_nop 1
	v_add_u32_dpp v12, v12, v12 row_ror:1 row_mask:0xf bank_mask:0xf bound_ctrl:1
	s_nop 0
	v_readlane_b32 s6, v12, 0
	v_readlane_b32 s7, v12, 16
	v_readlane_b32 s8, v12, 32
	v_readlane_b32 s9, v12, 48
	s_add_i32 s6, s6, s7
	s_add_i32 s8, s8, s9
	s_add_i32 s6, s6, s57
	s_add_i32 s8, s6, s8
	s_cmpk_eq_i32 s8, 0x100
	s_cbranch_scc1 .Lrdx_eq
	s_cmpk_lt_i32 s8, 0x100
	s_cselect_b32 s6, -1, 0
	s_cselect_b32 s57, s8, s57
	v_bitop3_b32 v7, v7, v132, s6 bitop3:0x60
	v_bitop3_b32 v6, v6, v129, s6 bitop3:0x60
	v_bitop3_b32 v5, v5, v59, s6 bitop3:0x60
	v_bitop3_b32 v4, v4, v54, s6 bitop3:0x60
	v_bitop3_b32 v3, v3, v8, s6 bitop3:0xf8
	v_bitop3_b32 v2, v2, v9, s6 bitop3:0xf8
	v_bitop3_b32 v1, v1, v10, s6 bitop3:0xf8
	v_bitop3_b32 v0, v0, v11, s6 bitop3:0xf8
	v_and_b32_e32 v8, v7, v130
	v_and_b32_e32 v9, v6, v127
	v_bcnt_u32_b32 v12, v8, 0
	v_and_b32_e32 v10, v5, v57
	v_bcnt_u32_b32 v12, v9, v12
	v_and_b32_e32 v11, v4, v52
	v_bcnt_u32_b32 v12, v10, v12
	v_bcnt_u32_b32 v12, v11, v12
	s_nop 1
	v_add_u32_dpp v12, v12, v12 row_ror:8 row_mask:0xf bank_mask:0xf bound_ctrl:1
	s_nop 1
	v_add_u32_dpp v12, v12, v12 row_ror:4 row_mask:0xf bank_mask:0xf bound_ctrl:1
	s_nop 1
	v_add_u32_dpp v12, v12, v12 row_ror:2 row_mask:0xf bank_mask:0xf bound_ctrl:1
	s_nop 1
	v_add_u32_dpp v12, v12, v12 row_ror:1 row_mask:0xf bank_mask:0xf bound_ctrl:1
	s_nop 0
	v_readlane_b32 s6, v12, 0
	v_readlane_b32 s7, v12, 16
	v_readlane_b32 s8, v12, 32
	v_readlane_b32 s9, v12, 48
	s_add_i32 s6, s6, s7
	s_add_i32 s8, s8, s9
	s_add_i32 s6, s6, s57
	s_add_i32 s8, s6, s8
	s_cmpk_eq_i32 s8, 0x100
	s_cbranch_scc1 .Lrdx_eq
	s_cmpk_lt_i32 s8, 0x100
	s_cselect_b32 s6, -1, 0
	s_cselect_b32 s57, s8, s57
	v_bitop3_b32 v7, v7, v130, s6 bitop3:0x60
	v_bitop3_b32 v6, v6, v127, s6 bitop3:0x60
	v_bitop3_b32 v5, v5, v57, s6 bitop3:0x60
	v_bitop3_b32 v4, v4, v52, s6 bitop3:0x60
	v_bitop3_b32 v3, v3, v8, s6 bitop3:0xf8
	v_bitop3_b32 v2, v2, v9, s6 bitop3:0xf8
	v_bitop3_b32 v1, v1, v10, s6 bitop3:0xf8
	v_bitop3_b32 v0, v0, v11, s6 bitop3:0xf8
	v_and_b32_e32 v8, v7, v128
	v_and_b32_e32 v9, v6, v125
	v_bcnt_u32_b32 v12, v8, 0
	v_and_b32_e32 v10, v5, v55
	v_bcnt_u32_b32 v12, v9, v12
	v_and_b32_e32 v11, v4, v50
	v_bcnt_u32_b32 v12, v10, v12
	v_bcnt_u32_b32 v12, v11, v12
	s_nop 1
	v_add_u32_dpp v12, v12, v12 row_ror:8 row_mask:0xf bank_mask:0xf bound_ctrl:1
	s_nop 1
	v_add_u32_dpp v12, v12, v12 row_ror:4 row_mask:0xf bank_mask:0xf bound_ctrl:1
	s_nop 1
	v_add_u32_dpp v12, v12, v12 row_ror:2 row_mask:0xf bank_mask:0xf bound_ctrl:1
	s_nop 1
	v_add_u32_dpp v12, v12, v12 row_ror:1 row_mask:0xf bank_mask:0xf bound_ctrl:1
	s_nop 0
	v_readlane_b32 s6, v12, 0
	v_readlane_b32 s7, v12, 16
	v_readlane_b32 s8, v12, 32
	v_readlane_b32 s9, v12, 48
	s_add_i32 s6, s6, s7
	s_add_i32 s8, s8, s9
	s_add_i32 s6, s6, s57
	s_add_i32 s8, s6, s8
	s_cmpk_eq_i32 s8, 0x100
	s_cbranch_scc1 .Lrdx_eq
	s_cmpk_lt_i32 s8, 0x100
	s_cselect_b32 s6, -1, 0
	s_cselect_b32 s57, s8, s57
	v_bitop3_b32 v7, v7, v128, s6 bitop3:0x60
	v_bitop3_b32 v6, v6, v125, s6 bitop3:0x60
	v_bitop3_b32 v5, v5, v55, s6 bitop3:0x60
	v_bitop3_b32 v4, v4, v50, s6 bitop3:0x60
	v_bitop3_b32 v3, v3, v8, s6 bitop3:0xf8
	v_bitop3_b32 v2, v2, v9, s6 bitop3:0xf8
	v_bitop3_b32 v1, v1, v10, s6 bitop3:0xf8
	v_bitop3_b32 v0, v0, v11, s6 bitop3:0xf8
	v_and_b32_e32 v8, v7, v126
	v_and_b32_e32 v9, v6, v123
	v_bcnt_u32_b32 v12, v8, 0
	v_and_b32_e32 v10, v5, v53
	v_bcnt_u32_b32 v12, v9, v12
	v_and_b32_e32 v11, v4, v48
	v_bcnt_u32_b32 v12, v10, v12
	v_bcnt_u32_b32 v12, v11, v12
	s_nop 1
	v_add_u32_dpp v12, v12, v12 row_ror:8 row_mask:0xf bank_mask:0xf bound_ctrl:1
	s_nop 1
	v_add_u32_dpp v12, v12, v12 row_ror:4 row_mask:0xf bank_mask:0xf bound_ctrl:1
	s_nop 1
	v_add_u32_dpp v12, v12, v12 row_ror:2 row_mask:0xf bank_mask:0xf bound_ctrl:1
	s_nop 1
	v_add_u32_dpp v12, v12, v12 row_ror:1 row_mask:0xf bank_mask:0xf bound_ctrl:1
	s_nop 0
	v_readlane_b32 s6, v12, 0
	v_readlane_b32 s7, v12, 16
	v_readlane_b32 s8, v12, 32
	v_readlane_b32 s9, v12, 48
	s_add_i32 s6, s6, s7
	s_add_i32 s8, s8, s9
	s_add_i32 s6, s6, s57
	s_add_i32 s8, s6, s8
	s_cmpk_eq_i32 s8, 0x100
	s_cbranch_scc1 .Lrdx_eq
	s_cmpk_lt_i32 s8, 0x100
	s_cselect_b32 s6, -1, 0
	s_cselect_b32 s57, s8, s57
	v_bitop3_b32 v7, v7, v126, s6 bitop3:0x60
	v_bitop3_b32 v6, v6, v123, s6 bitop3:0x60
	v_bitop3_b32 v5, v5, v53, s6 bitop3:0x60
	v_bitop3_b32 v4, v4, v48, s6 bitop3:0x60
	v_bitop3_b32 v3, v3, v8, s6 bitop3:0xf8
	v_bitop3_b32 v2, v2, v9, s6 bitop3:0xf8
	v_bitop3_b32 v1, v1, v10, s6 bitop3:0xf8
	v_bitop3_b32 v0, v0, v11, s6 bitop3:0xf8
	v_and_b32_e32 v8, v7, v124
	v_and_b32_e32 v9, v6, v121
	v_bcnt_u32_b32 v12, v8, 0
	v_and_b32_e32 v10, v5, v51
	v_bcnt_u32_b32 v12, v9, v12
	v_and_b32_e32 v11, v4, v46
	v_bcnt_u32_b32 v12, v10, v12
	v_bcnt_u32_b32 v12, v11, v12
	s_nop 1
	v_add_u32_dpp v12, v12, v12 row_ror:8 row_mask:0xf bank_mask:0xf bound_ctrl:1
	s_nop 1
	v_add_u32_dpp v12, v12, v12 row_ror:4 row_mask:0xf bank_mask:0xf bound_ctrl:1
	s_nop 1
	v_add_u32_dpp v12, v12, v12 row_ror:2 row_mask:0xf bank_mask:0xf bound_ctrl:1
	s_nop 1
	v_add_u32_dpp v12, v12, v12 row_ror:1 row_mask:0xf bank_mask:0xf bound_ctrl:1
	s_nop 0
	v_readlane_b32 s6, v12, 0
	v_readlane_b32 s7, v12, 16
	v_readlane_b32 s8, v12, 32
	v_readlane_b32 s9, v12, 48
	s_add_i32 s6, s6, s7
	s_add_i32 s8, s8, s9
	s_add_i32 s6, s6, s57
	s_add_i32 s8, s6, s8
	s_cmpk_eq_i32 s8, 0x100
	s_cbranch_scc1 .Lrdx_eq
	s_cmpk_lt_i32 s8, 0x100
	s_cselect_b32 s6, -1, 0
	s_cselect_b32 s57, s8, s57
	v_bitop3_b32 v7, v7, v124, s6 bitop3:0x60
	v_bitop3_b32 v6, v6, v121, s6 bitop3:0x60
	v_bitop3_b32 v5, v5, v51, s6 bitop3:0x60
	v_bitop3_b32 v4, v4, v46, s6 bitop3:0x60
	v_bitop3_b32 v3, v3, v8, s6 bitop3:0xf8
	v_bitop3_b32 v2, v2, v9, s6 bitop3:0xf8
	v_bitop3_b32 v1, v1, v10, s6 bitop3:0xf8
	v_bitop3_b32 v0, v0, v11, s6 bitop3:0xf8
	v_and_b32_e32 v8, v7, v122
	v_and_b32_e32 v9, v6, v119
	v_bcnt_u32_b32 v12, v8, 0
	v_and_b32_e32 v10, v5, v49
	v_bcnt_u32_b32 v12, v9, v12
	v_and_b32_e32 v11, v4, v44
	v_bcnt_u32_b32 v12, v10, v12
	v_bcnt_u32_b32 v12, v11, v12
	s_nop 1
	v_add_u32_dpp v12, v12, v12 row_ror:8 row_mask:0xf bank_mask:0xf bound_ctrl:1
	s_nop 1
	v_add_u32_dpp v12, v12, v12 row_ror:4 row_mask:0xf bank_mask:0xf bound_ctrl:1
	s_nop 1
	v_add_u32_dpp v12, v12, v12 row_ror:2 row_mask:0xf bank_mask:0xf bound_ctrl:1
	s_nop 1
	v_add_u32_dpp v12, v12, v12 row_ror:1 row_mask:0xf bank_mask:0xf bound_ctrl:1
	s_nop 0
	v_readlane_b32 s6, v12, 0
	v_readlane_b32 s7, v12, 16
	v_readlane_b32 s8, v12, 32
	v_readlane_b32 s9, v12, 48
	s_add_i32 s6, s6, s7
	s_add_i32 s8, s8, s9
	s_add_i32 s6, s6, s57
	s_add_i32 s8, s6, s8
	s_cmpk_eq_i32 s8, 0x100
	s_cbranch_scc1 .Lrdx_eq
	s_cmpk_lt_i32 s8, 0x100
	s_cselect_b32 s6, -1, 0
	s_cselect_b32 s57, s8, s57
	v_bitop3_b32 v7, v7, v122, s6 bitop3:0x60
	v_bitop3_b32 v6, v6, v119, s6 bitop3:0x60
	v_bitop3_b32 v5, v5, v49, s6 bitop3:0x60
	v_bitop3_b32 v4, v4, v44, s6 bitop3:0x60
	v_bitop3_b32 v3, v3, v8, s6 bitop3:0xf8
	v_bitop3_b32 v2, v2, v9, s6 bitop3:0xf8
	v_bitop3_b32 v1, v1, v10, s6 bitop3:0xf8
	v_bitop3_b32 v0, v0, v11, s6 bitop3:0xf8
	v_and_b32_e32 v8, v7, v120
	v_and_b32_e32 v9, v6, v117
	v_bcnt_u32_b32 v12, v8, 0
	v_and_b32_e32 v10, v5, v47
	v_bcnt_u32_b32 v12, v9, v12
	v_and_b32_e32 v11, v4, v43
	v_bcnt_u32_b32 v12, v10, v12
	v_bcnt_u32_b32 v12, v11, v12
	s_nop 1
	v_add_u32_dpp v12, v12, v12 row_ror:8 row_mask:0xf bank_mask:0xf bound_ctrl:1
	s_nop 1
	v_add_u32_dpp v12, v12, v12 row_ror:4 row_mask:0xf bank_mask:0xf bound_ctrl:1
	s_nop 1
	v_add_u32_dpp v12, v12, v12 row_ror:2 row_mask:0xf bank_mask:0xf bound_ctrl:1
	s_nop 1
	v_add_u32_dpp v12, v12, v12 row_ror:1 row_mask:0xf bank_mask:0xf bound_ctrl:1
	s_nop 0
	v_readlane_b32 s6, v12, 0
	v_readlane_b32 s7, v12, 16
	v_readlane_b32 s8, v12, 32
	v_readlane_b32 s9, v12, 48
	s_add_i32 s6, s6, s7
	s_add_i32 s8, s8, s9
	s_add_i32 s6, s6, s57
	s_add_i32 s8, s6, s8
	s_cmpk_eq_i32 s8, 0x100
	s_cbranch_scc1 .Lrdx_eq
	s_cmpk_lt_i32 s8, 0x100
	s_cselect_b32 s6, -1, 0
	s_cselect_b32 s57, s8, s57
	v_bitop3_b32 v7, v7, v120, s6 bitop3:0x60
	v_bitop3_b32 v6, v6, v117, s6 bitop3:0x60
	v_bitop3_b32 v5, v5, v47, s6 bitop3:0x60
	v_bitop3_b32 v4, v4, v43, s6 bitop3:0x60
	v_bitop3_b32 v3, v3, v8, s6 bitop3:0xf8
	v_bitop3_b32 v2, v2, v9, s6 bitop3:0xf8
	v_bitop3_b32 v1, v1, v10, s6 bitop3:0xf8
	v_bitop3_b32 v0, v0, v11, s6 bitop3:0xf8
	v_and_b32_e32 v8, v7, v118
	v_and_b32_e32 v9, v6, v115
	v_bcnt_u32_b32 v12, v8, 0
	v_and_b32_e32 v10, v5, v45
	v_bcnt_u32_b32 v12, v9, v12
	v_and_b32_e32 v11, v4, v41
	v_bcnt_u32_b32 v12, v10, v12
	v_bcnt_u32_b32 v12, v11, v12
	s_nop 1
	v_add_u32_dpp v12, v12, v12 row_ror:8 row_mask:0xf bank_mask:0xf bound_ctrl:1
	s_nop 1
	v_add_u32_dpp v12, v12, v12 row_ror:4 row_mask:0xf bank_mask:0xf bound_ctrl:1
	s_nop 1
	v_add_u32_dpp v12, v12, v12 row_ror:2 row_mask:0xf bank_mask:0xf bound_ctrl:1
	s_nop 1
	v_add_u32_dpp v12, v12, v12 row_ror:1 row_mask:0xf bank_mask:0xf bound_ctrl:1
	s_nop 0
	v_readlane_b32 s6, v12, 0
	v_readlane_b32 s7, v12, 16
	v_readlane_b32 s8, v12, 32
	v_readlane_b32 s9, v12, 48
	s_add_i32 s6, s6, s7
	s_add_i32 s8, s8, s9
	s_add_i32 s6, s6, s57
	s_add_i32 s8, s6, s8
	s_cmpk_eq_i32 s8, 0x100
	s_cbranch_scc1 .Lrdx_eq
	s_cmpk_lt_i32 s8, 0x100
	s_cselect_b32 s6, -1, 0
	s_cselect_b32 s57, s8, s57
	v_bitop3_b32 v7, v7, v118, s6 bitop3:0x60
	v_bitop3_b32 v6, v6, v115, s6 bitop3:0x60
	v_bitop3_b32 v5, v5, v45, s6 bitop3:0x60
	v_bitop3_b32 v4, v4, v41, s6 bitop3:0x60
	v_bitop3_b32 v3, v3, v8, s6 bitop3:0xf8
	v_bitop3_b32 v2, v2, v9, s6 bitop3:0xf8
	v_bitop3_b32 v1, v1, v10, s6 bitop3:0xf8
	v_bitop3_b32 v0, v0, v11, s6 bitop3:0xf8
	v_and_b32_e32 v8, v7, v116
	v_and_b32_e32 v9, v6, v113
	v_bcnt_u32_b32 v12, v8, 0
	v_and_b32_e32 v10, v5, v42
	v_bcnt_u32_b32 v12, v9, v12
	v_and_b32_e32 v11, v4, v39
	v_bcnt_u32_b32 v12, v10, v12
	v_bcnt_u32_b32 v12, v11, v12
	s_nop 1
	v_add_u32_dpp v12, v12, v12 row_ror:8 row_mask:0xf bank_mask:0xf bound_ctrl:1
	s_nop 1
	v_add_u32_dpp v12, v12, v12 row_ror:4 row_mask:0xf bank_mask:0xf bound_ctrl:1
	s_nop 1
	v_add_u32_dpp v12, v12, v12 row_ror:2 row_mask:0xf bank_mask:0xf bound_ctrl:1
	s_nop 1
	v_add_u32_dpp v12, v12, v12 row_ror:1 row_mask:0xf bank_mask:0xf bound_ctrl:1
	s_nop 0
	v_readlane_b32 s6, v12, 0
	v_readlane_b32 s7, v12, 16
	v_readlane_b32 s8, v12, 32
	v_readlane_b32 s9, v12, 48
	s_add_i32 s6, s6, s7
	s_add_i32 s8, s8, s9
	s_add_i32 s6, s6, s57
	s_add_i32 s8, s6, s8
	s_cmpk_eq_i32 s8, 0x100
	s_cbranch_scc1 .Lrdx_eq
	s_cmpk_lt_i32 s8, 0x100
	s_cselect_b32 s6, -1, 0
	s_cselect_b32 s57, s8, s57
	v_bitop3_b32 v7, v7, v116, s6 bitop3:0x60
	v_bitop3_b32 v6, v6, v113, s6 bitop3:0x60
	v_bitop3_b32 v5, v5, v42, s6 bitop3:0x60
	v_bitop3_b32 v4, v4, v39, s6 bitop3:0x60
	v_bitop3_b32 v3, v3, v8, s6 bitop3:0xf8
	v_bitop3_b32 v2, v2, v9, s6 bitop3:0xf8
	v_bitop3_b32 v1, v1, v10, s6 bitop3:0xf8
	v_bitop3_b32 v0, v0, v11, s6 bitop3:0xf8
	v_and_b32_e32 v8, v7, v114
	v_and_b32_e32 v9, v6, v111
	v_bcnt_u32_b32 v12, v8, 0
	v_and_b32_e32 v10, v5, v40
	v_bcnt_u32_b32 v12, v9, v12
	v_and_b32_e32 v11, v4, v37
	v_bcnt_u32_b32 v12, v10, v12
	v_bcnt_u32_b32 v12, v11, v12
	s_nop 1
	v_add_u32_dpp v12, v12, v12 row_ror:8 row_mask:0xf bank_mask:0xf bound_ctrl:1
	s_nop 1
	v_add_u32_dpp v12, v12, v12 row_ror:4 row_mask:0xf bank_mask:0xf bound_ctrl:1
	s_nop 1
	v_add_u32_dpp v12, v12, v12 row_ror:2 row_mask:0xf bank_mask:0xf bound_ctrl:1
	s_nop 1
	v_add_u32_dpp v12, v12, v12 row_ror:1 row_mask:0xf bank_mask:0xf bound_ctrl:1
	s_nop 0
	v_readlane_b32 s6, v12, 0
	v_readlane_b32 s7, v12, 16
	v_readlane_b32 s8, v12, 32
	v_readlane_b32 s9, v12, 48
	s_add_i32 s6, s6, s7
	s_add_i32 s8, s8, s9
	s_add_i32 s6, s6, s57
	s_add_i32 s8, s6, s8
	s_cmpk_eq_i32 s8, 0x100
	s_cbranch_scc1 .Lrdx_eq
	s_cmpk_lt_i32 s8, 0x100
	s_cselect_b32 s6, -1, 0
	s_cselect_b32 s57, s8, s57
	v_bitop3_b32 v7, v7, v114, s6 bitop3:0x60
	v_bitop3_b32 v6, v6, v111, s6 bitop3:0x60
	v_bitop3_b32 v5, v5, v40, s6 bitop3:0x60
	v_bitop3_b32 v4, v4, v37, s6 bitop3:0x60
	v_bitop3_b32 v3, v3, v8, s6 bitop3:0xf8
	v_bitop3_b32 v2, v2, v9, s6 bitop3:0xf8
	v_bitop3_b32 v1, v1, v10, s6 bitop3:0xf8
	v_bitop3_b32 v0, v0, v11, s6 bitop3:0xf8
	v_and_b32_e32 v8, v7, v112
	v_and_b32_e32 v9, v6, v109
	v_bcnt_u32_b32 v12, v8, 0
	v_and_b32_e32 v10, v5, v38
	v_bcnt_u32_b32 v12, v9, v12
	v_and_b32_e32 v11, v4, v35
	v_bcnt_u32_b32 v12, v10, v12
	v_bcnt_u32_b32 v12, v11, v12
	s_nop 1
	v_add_u32_dpp v12, v12, v12 row_ror:8 row_mask:0xf bank_mask:0xf bound_ctrl:1
	s_nop 1
	v_add_u32_dpp v12, v12, v12 row_ror:4 row_mask:0xf bank_mask:0xf bound_ctrl:1
	s_nop 1
	v_add_u32_dpp v12, v12, v12 row_ror:2 row_mask:0xf bank_mask:0xf bound_ctrl:1
	s_nop 1
	v_add_u32_dpp v12, v12, v12 row_ror:1 row_mask:0xf bank_mask:0xf bound_ctrl:1
	s_nop 0
	v_readlane_b32 s6, v12, 0
	v_readlane_b32 s7, v12, 16
	v_readlane_b32 s8, v12, 32
	v_readlane_b32 s9, v12, 48
	s_add_i32 s6, s6, s7
	s_add_i32 s8, s8, s9
	s_add_i32 s6, s6, s57
	s_add_i32 s8, s6, s8
	s_cmpk_eq_i32 s8, 0x100
	s_cbranch_scc1 .Lrdx_eq
	s_cmpk_lt_i32 s8, 0x100
	s_cselect_b32 s6, -1, 0
	s_cselect_b32 s57, s8, s57
	v_bitop3_b32 v7, v7, v112, s6 bitop3:0x60
	v_bitop3_b32 v6, v6, v109, s6 bitop3:0x60
	v_bitop3_b32 v5, v5, v38, s6 bitop3:0x60
	v_bitop3_b32 v4, v4, v35, s6 bitop3:0x60
	v_bitop3_b32 v3, v3, v8, s6 bitop3:0xf8
	v_bitop3_b32 v2, v2, v9, s6 bitop3:0xf8
	v_bitop3_b32 v1, v1, v10, s6 bitop3:0xf8
	v_bitop3_b32 v0, v0, v11, s6 bitop3:0xf8
	v_and_b32_e32 v8, v7, v110
	v_and_b32_e32 v9, v6, v107
	v_bcnt_u32_b32 v12, v8, 0
	v_and_b32_e32 v10, v5, v36
	v_bcnt_u32_b32 v12, v9, v12
	v_and_b32_e32 v11, v4, v33
	v_bcnt_u32_b32 v12, v10, v12
	v_bcnt_u32_b32 v12, v11, v12
	s_nop 1
	v_add_u32_dpp v12, v12, v12 row_ror:8 row_mask:0xf bank_mask:0xf bound_ctrl:1
	s_nop 1
	v_add_u32_dpp v12, v12, v12 row_ror:4 row_mask:0xf bank_mask:0xf bound_ctrl:1
	s_nop 1
	v_add_u32_dpp v12, v12, v12 row_ror:2 row_mask:0xf bank_mask:0xf bound_ctrl:1
	s_nop 1
	v_add_u32_dpp v12, v12, v12 row_ror:1 row_mask:0xf bank_mask:0xf bound_ctrl:1
	s_nop 0
	v_readlane_b32 s6, v12, 0
	v_readlane_b32 s7, v12, 16
	v_readlane_b32 s8, v12, 32
	v_readlane_b32 s9, v12, 48
	s_add_i32 s6, s6, s7
	s_add_i32 s8, s8, s9
	s_add_i32 s6, s6, s57
	s_add_i32 s8, s6, s8
	s_cmpk_eq_i32 s8, 0x100
	s_cbranch_scc1 .Lrdx_eq
	s_cmpk_lt_i32 s8, 0x100
	s_cselect_b32 s6, -1, 0
	s_cselect_b32 s57, s8, s57
	v_bitop3_b32 v7, v7, v110, s6 bitop3:0x60
	v_bitop3_b32 v6, v6, v107, s6 bitop3:0x60
	v_bitop3_b32 v5, v5, v36, s6 bitop3:0x60
	v_bitop3_b32 v4, v4, v33, s6 bitop3:0x60
	v_bitop3_b32 v3, v3, v8, s6 bitop3:0xf8
	v_bitop3_b32 v2, v2, v9, s6 bitop3:0xf8
	v_bitop3_b32 v1, v1, v10, s6 bitop3:0xf8
	v_bitop3_b32 v0, v0, v11, s6 bitop3:0xf8
	v_and_b32_e32 v8, v7, v108
	v_and_b32_e32 v9, v6, v106
	v_bcnt_u32_b32 v12, v8, 0
	v_and_b32_e32 v10, v5, v34
	v_bcnt_u32_b32 v12, v9, v12
	v_and_b32_e32 v11, v4, v32
	v_bcnt_u32_b32 v12, v10, v12
	v_bcnt_u32_b32 v12, v11, v12
	s_nop 1
	v_add_u32_dpp v12, v12, v12 row_ror:8 row_mask:0xf bank_mask:0xf bound_ctrl:1
	s_nop 1
	v_add_u32_dpp v12, v12, v12 row_ror:4 row_mask:0xf bank_mask:0xf bound_ctrl:1
	s_nop 1
	v_add_u32_dpp v12, v12, v12 row_ror:2 row_mask:0xf bank_mask:0xf bound_ctrl:1
	s_nop 1
	v_add_u32_dpp v12, v12, v12 row_ror:1 row_mask:0xf bank_mask:0xf bound_ctrl:1
	s_nop 0
	v_readlane_b32 s6, v12, 0
	v_readlane_b32 s7, v12, 16
	v_readlane_b32 s8, v12, 32
	v_readlane_b32 s9, v12, 48
	s_add_i32 s6, s6, s7
	s_add_i32 s8, s8, s9
	s_add_i32 s6, s6, s57
	s_add_i32 s8, s6, s8
	s_cmpk_eq_i32 s8, 0x100
	s_cbranch_scc1 .Lrdx_eq
	s_cmpk_lt_i32 s8, 0x100
	s_cselect_b32 s6, -1, 0
	s_cselect_b32 s57, s8, s57
	v_bitop3_b32 v7, v7, v108, s6 bitop3:0x60
	v_bitop3_b32 v6, v6, v106, s6 bitop3:0x60
	v_bitop3_b32 v5, v5, v34, s6 bitop3:0x60
	v_bitop3_b32 v4, v4, v32, s6 bitop3:0x60
	v_bitop3_b32 v3, v3, v8, s6 bitop3:0xf8
	v_bitop3_b32 v2, v2, v9, s6 bitop3:0xf8
	v_bitop3_b32 v1, v1, v10, s6 bitop3:0xf8
	v_bitop3_b32 v0, v0, v11, s6 bitop3:0xf8
	s_branch .LBB0_1099
.Lrdx_eq:
	v_or_b32_e32 v3, v3, v8
	v_or_b32_e32 v2, v2, v9
	v_or_b32_e32 v1, v1, v10
	v_or_b32_e32 v0, v0, v11
	s_movk_i32 s57, 0x100
	v_mov_b32_e32 v7, 0
	v_mov_b32_e32 v6, 0
	v_mov_b32_e32 v5, 0
	v_mov_b32_e32 v4, 0
